# first-iteration peel generalized (first touch by C operand) and applied to the second SSM GEMM loop as well
# speedup vs baseline: 1.0026x; 1.0026x over previous
;     ...
;     f32x4 acc[2][2][4][2];
; #pragma unroll
;     for (int a = 0; a < 2; ++a)
; #pragma unroll
;         for (int b = 0; b < 2; ++b)
; #pragma unroll
;             for (int m = 0; m < 4; ++m)
; #pragma unroll
;                 for (int n = 0; n < 2; ++n) acc[a][b][m][n] = (f32x4){0.f, 0.f, 0.f, 0.f};
;     bf16x8 At[4][2], B0[2][2], B1[2][2];
;     const char* cA = cur.A; const char* cB = cur.B;
;     G_STAGE(G_SB(0, 0), cB, cB0, qB); G_STAGE(G_SA(0, 0), cA, cA0, qA); G_STAGE(G_SB(0, 1), cB + chB, cB0, qB); G_STAGE(G_SA(0, 1), cA + chA, cA0, qA);
;     if (wr == 1) G_BAR;
;     G_WAIT_V(4); G_BAR;
;     G_STAGE(G_SB(1, 0), cB + kB, cB0, qB); G_STAGE(G_SA(1, 0), cA + ckA, cA0, qA); G_STAGE(G_SB(1, 1), cB + chB + kB, cB0, qB);
;     G_WAIT_V(6); G_BAR;
;     for (;;) {
;         const bool has_next = sched_next<PH, SUB>(E.ws, E.layer, ui + 1, nxt, E.x);
;         if (!has_next) nxt = cur;
;         const char* nA = nxt.A; const char* nB = nxt.B;
; #pragma unroll 1
;         for (int t = 0; t < nt; t += 2) {
;             const bool last = (t == nt - 2);
;             const char* a1 = cA + (size_t)(t + 1) * ckA;
;             const char* a2 = last ? nA : cA + (size_t)(t + 2) * ckA; const char* b2 = last ? nB : cB + (size_t)(t + 2) * kB;
;             const char* a3 = a2 + ckA; const char* b3 = b2 + kB;
;             G_LDB(B0, 0, 0); G_SCHED; G_LDA(At, 0, 0); G_STAGE(G_SA(1, 1), a1 + chA, cA0, qA);
;             G_WAIT_L(8); G_BAR; G_WAIT_L(0); G_MMA(0, 0, At, B0); G_BAR; G_SCHED;
;             G_LDB(B1, 0, 1); G_STAGE(G_SB(0, 0), b2, cB0, qB);
;             G_BAR; G_WAIT_L(0); G_MMA(0, 1, At, B1); G_BAR;
;             G_LDA(At, 0, 1); G_STAGE(G_SA(0, 0), a2, cA0, qA);
;             G_BAR; G_WAIT_L(0); G_MMA(1, 0, At, B0); G_BAR; G_SCHED;
;             G_STAGE(G_SB(0, 1), b2 + chB, cB0, qB);
;             G_WAIT_V(6); G_BAR; G_MMA(1, 1, At, B1); G_BAR;
;             G_LDB(B0, 1, 0); G_SCHED; G_LDA(At, 1, 0); G_STAGE(G_SA(0, 1), a2 + chA, cA0, qA);
;             G_WAIT_L(8); G_BAR; G_WAIT_L(0); G_MMA(0, 0, At, B0); G_BAR; G_SCHED;
;             G_LDB(B1, 1, 1); G_STAGE(G_SB(1, 0), b3, cB0, qB);
;             G_BAR; G_WAIT_L(0); G_MMA(0, 1, At, B1); G_BAR;
;             G_LDA(At, 1, 1); G_STAGE(G_SA(1, 0), a3, cA0, qA);
;             G_BAR; G_WAIT_L(0); G_MMA(1, 0, At, B0); G_BAR; G_SCHED;
;             G_STAGE(G_SB(1, 1), b3 + chB, cB0, qB);
.LBB0_741:
	s_mov_b64 s[30:31], 0
	s_mov_b64 s[24:25], -1
	s_mov_b64 s[26:27], 0
	s_mov_b64 s[82:83], 0x10000
	s_mov_b64 s[84:85], 0x10080
	s_mov_b64 s[86:87], 0x200000
	s_mov_b64 s[88:89], 0x100000
	s_mov_b64 s[92:93], 0x8000
	s_mov_b64 s[94:95], 0x18000
	s_mov_b64 s[96:97], 0x300000
	s_mov_b64 s[70:71], 0x8080
	s_mov_b64 s[68:69], 0x100080
	s_mov_b64 s[28:29], 0x18080
	s_cmp_eq_u32 s101, 2
	s_cselect_b32 s101, 0, s101
	s_setprio 0
	v_add_u32_e32 v255, 0x10000, v183
	s_add_u32 s36, s2, s30
	s_addc_u32 s37, s3, s31
	s_add_u32 s19, s36, 0x100
	s_addc_u32 s35, s37, 0
	s_and_b64 s[4:5], s[26:27], exec
	s_cselect_b32 s34, s12, s19
	s_cselect_b32 s35, s13, s35
	s_add_u32 s4, s20, s30
	s_addc_u32 s5, s21, s31
	s_add_u32 s19, s4, 0x100
	s_addc_u32 s30, s5, 0
	s_add_i32 s44, 0, 0x10000
	ds_read_b128 v[56:59], v255 offset:0
	ds_read_b128 v[60:63], v255 offset:1024
	ds_read_b128 v[144:147], v255 offset:2048
	ds_read_b128 v[148:151], v255 offset:3072
	s_and_b64 s[4:5], s[26:27], exec
	s_cselect_b32 s26, s16, s19
	s_cselect_b32 s27, s17, s30
	s_add_i32 s48, 0, 0x14000
	s_add_i32 s31, 0, 0x18000
	s_add_i32 s19, 0, 0x1c000
	s_add_i32 s49, s44, s38
	s_add_i32 s63, s48, s38
	s_add_i32 s30, s31, s38
	s_add_i32 s65, s19, s38
	s_add_i32 m0, s43, 0xc000
	s_add_i32 s45, s43, 0xe000
	s_add_i32 s66, s49, 0x2000
	s_add_i32 s62, s63, 0x2000
	s_add_i32 s67, s30, 0x2000
	s_add_i32 s64, s65, 0x2000
	s_mov_b64 s[4:5], 0x200080
	s_add_u32 vcc_lo, s36, s4
	s_addc_u32 vcc_hi, s37, s5
	s_mov_b64 s[4:5], 0x300080
	ds_read_b128 v[152:155], v184
	ds_read_b128 v[156:159], v184 offset:1024
	ds_read_b128 v[162:165], v184 offset:2048
	ds_read_b128 v[172:175], v184 offset:3072
	ds_read_b128 v[176:179], v184 offset:4096
	ds_read_b128 v[196:199], v184 offset:5120
	ds_read_b128 v[200:203], v184 offset:6144
	ds_read_b128 v[204:207], v184 offset:7168
	global_load_lds_dwordx4 v160, vcc
	s_mov_b32 m0, s45
	s_nop 0
	s_add_u32 vcc_lo, s36, s4
	s_addc_u32 vcc_hi, s37, s5
	global_load_lds_dwordx4 v160, vcc
	s_waitcnt lgkmcnt(8)
	s_cmp_eq_u32 s101, 1
	s_cbranch_scc1 .Ldb_SSM2_skp
	s_barrier
.Ldb_SSM2_skp:
	s_mov_b32 s101, 0
	s_waitcnt lgkmcnt(0)
	v_mfma_f32_16x16x32_bf16 v[140:143], v[56:59], v[152:155], 0
	v_mfma_f32_16x16x32_bf16 v[136:139], v[144:147], v[152:155], 0
	v_mfma_f32_16x16x32_bf16 v[124:127], v[56:59], v[162:165], 0
	v_mfma_f32_16x16x32_bf16 v[120:123], v[144:147], v[162:165], 0
	v_mfma_f32_16x16x32_bf16 v[108:111], v[56:59], v[176:179], 0
	v_mfma_f32_16x16x32_bf16 v[104:107], v[144:147], v[176:179], 0
	v_mfma_f32_16x16x32_bf16 v[92:95], v[56:59], v[200:203], 0
	v_mfma_f32_16x16x32_bf16 v[88:91], v[144:147], v[200:203], 0
	v_mfma_f32_16x16x32_bf16 v[140:143], v[60:63], v[156:159], v[140:143]
	v_mfma_f32_16x16x32_bf16 v[136:139], v[148:151], v[156:159], v[136:139]
	v_mfma_f32_16x16x32_bf16 v[124:127], v[60:63], v[172:175], v[124:127]
	v_mfma_f32_16x16x32_bf16 v[120:123], v[148:151], v[172:175], v[120:123]
	v_mfma_f32_16x16x32_bf16 v[108:111], v[60:63], v[196:199], v[108:111]
	v_mfma_f32_16x16x32_bf16 v[104:107], v[148:151], v[196:199], v[104:107]
	v_mfma_f32_16x16x32_bf16 v[92:95], v[60:63], v[204:207], v[92:95]
	v_mfma_f32_16x16x32_bf16 v[88:91], v[148:151], v[204:207], v[88:91]
	s_barrier
	s_mov_b32 m0, s49
	ds_read_b128 v[208:211], v255 offset:16384
	ds_read_b128 v[212:215], v255 offset:17408
	ds_read_b128 v[216:219], v255 offset:18432
	ds_read_b128 v[220:223], v255 offset:19456
	global_load_lds_dwordx4 v2, s[26:27]
	s_mov_b32 m0, s66
	s_nop 0
	s_add_u32 vcc_lo, s26, s92
	s_addc_u32 vcc_hi, s27, s93
	global_load_lds_dwordx4 v2, vcc
	s_barrier
	s_waitcnt lgkmcnt(0)
	v_mfma_f32_16x16x32_bf16 v[132:135], v[208:211], v[152:155], 0
	v_mfma_f32_16x16x32_bf16 v[128:131], v[216:219], v[152:155], 0
	v_mfma_f32_16x16x32_bf16 v[116:119], v[208:211], v[162:165], 0
	v_mfma_f32_16x16x32_bf16 v[112:115], v[216:219], v[162:165], 0
	v_mfma_f32_16x16x32_bf16 v[100:103], v[208:211], v[176:179], 0
	v_mfma_f32_16x16x32_bf16 v[96:99], v[216:219], v[176:179], 0
	v_mfma_f32_16x16x32_bf16 v[84:87], v[208:211], v[200:203], 0
	v_mfma_f32_16x16x32_bf16 v[80:83], v[216:219], v[200:203], 0
	v_mfma_f32_16x16x32_bf16 v[132:135], v[212:215], v[156:159], v[132:135]
	v_mfma_f32_16x16x32_bf16 v[128:131], v[220:223], v[156:159], v[128:131]
	v_mfma_f32_16x16x32_bf16 v[116:119], v[212:215], v[172:175], v[116:119]
	v_mfma_f32_16x16x32_bf16 v[112:115], v[220:223], v[172:175], v[112:115]
	v_mfma_f32_16x16x32_bf16 v[100:103], v[212:215], v[196:199], v[100:103]
	v_mfma_f32_16x16x32_bf16 v[96:99], v[220:223], v[196:199], v[96:99]
	v_mfma_f32_16x16x32_bf16 v[84:87], v[212:215], v[204:207], v[84:87]
	v_mfma_f32_16x16x32_bf16 v[80:83], v[220:223], v[204:207], v[80:83]
	s_barrier
	s_mov_b32 m0, s43
	ds_read_b128 v[152:155], v184 offset:16384
	ds_read_b128 v[156:159], v184 offset:17408
	ds_read_b128 v[162:165], v184 offset:18432
	ds_read_b128 v[172:175], v184 offset:19456
	ds_read_b128 v[176:179], v184 offset:20480
	ds_read_b128 v[196:199], v184 offset:21504
	ds_read_b128 v[200:203], v184 offset:22528
	ds_read_b128 v[204:207], v184 offset:23552
	global_load_lds_dwordx4 v160, s[34:35]
	s_mov_b32 m0, s50
	s_nop 0
	s_add_u32 vcc_lo, s34, s88
	s_addc_u32 vcc_hi, s35, s89
	global_load_lds_dwordx4 v160, vcc
	s_barrier
; #define G_STAGE(bufoff, gbase, o0, h64) do { \
;         __builtin_amdgcn_global_load_lds((const unsigned*)((const char*)(gbase) + (o0)), (LAS unsigned*)(lds + (bufoff) + ldsw), 16, 0, 0); \
;         __builtin_amdgcn_global_load_lds((const unsigned*)((const char*)(gbase) + (h64) + (o0)), (LAS unsigned*)(lds + (bufoff) + ldsw + 8192), 16, 0, 0); } while (0)
; #define G_LDA(dst, b, h) do { _Pragma("unroll") for (int m = 0; m < 4; ++m) _Pragma("unroll") for (int k = 0; k < 2; ++k) dst[m][k] = *(const LAS bf16x8*)(lds + G_SA(b, h) + aoff + m * 2048 + k * 1024); } while (0)
; #define G_LDB(dst, b, h) do { _Pragma("unroll") for (int n = 0; n < 2; ++n) _Pragma("unroll") for (int k = 0; k < 2; ++k) dst[n][k] = *(const LAS bf16x8*)(lds + G_SB(b, h) + boff + n * 2048 + k * 1024); } while (0)
; #define G_WAIT_V(n) asm volatile("s_waitcnt vmcnt(" #n ")" ::: "memory")
; #define G_BAR __builtin_amdgcn_s_barrier()
;     ...
;         for (int t = 0; t < nt; t += 2) {
;             const bool last = (t == nt - 2);
;             const char* a1 = cA + (size_t)(t + 1) * ckA;
;             const char* a2 = last ? nA : cA + (size_t)(t + 2) * ckA; const char* b2 = last ? nB : cB + (size_t)(t + 2) * kB;
;             const char* a3 = a2 + ckA; const char* b3 = b2 + kB;
;             G_LDB(B0, 0, 0); G_SCHED; G_LDA(At, 0, 0); G_STAGE(G_SA(1, 1), a1 + chA, cA0, qA);
;             G_WAIT_L(8); G_BAR; G_WAIT_L(0); G_MMA(0, 0, At, B0); G_BAR; G_SCHED;
;             G_LDB(B1, 0, 1); G_STAGE(G_SB(0, 0), b2, cB0, qB);
;             G_BAR; G_WAIT_L(0); G_MMA(0, 1, At, B1); G_BAR;
;             G_LDA(At, 0, 1); G_STAGE(G_SA(0, 0), a2, cA0, qA);
;             G_BAR; G_WAIT_L(0); G_MMA(1, 0, At, B0); G_BAR; G_SCHED;
;             G_STAGE(G_SB(0, 1), b2 + chB, cB0, qB);
;             G_WAIT_V(6); G_BAR; G_MMA(1, 1, At, B1); G_BAR;
;             G_LDB(B0, 1, 0); G_SCHED; G_LDA(At, 1, 0); G_STAGE(G_SA(0, 1), a2 + chA, cA0, qA);
;             G_WAIT_L(8); G_BAR; G_WAIT_L(0); G_MMA(0, 0, At, B0); G_BAR; G_SCHED;
;             G_LDB(B1, 1, 1); G_STAGE(G_SB(1, 0), b3, cB0, qB);
;             G_BAR; G_WAIT_L(0); G_MMA(0, 1, At, B1); G_BAR;
;             G_LDA(At, 1, 1); G_STAGE(G_SA(1, 0), a3, cA0, qA);
;             G_BAR; G_WAIT_L(0); G_MMA(1, 0, At, B0); G_BAR; G_SCHED;
;             G_STAGE(G_SB(1, 1), b3 + chB, cB0, qB);
;             G_WAIT_V(6); G_BAR; G_MMA(1, 1, At, B1); G_BAR;
	s_waitcnt lgkmcnt(0)
	v_mfma_f32_16x16x32_bf16 v[76:79], v[56:59], v[152:155], 0
	v_mfma_f32_16x16x32_bf16 v[72:75], v[144:147], v[152:155], 0
	v_mfma_f32_16x16x32_bf16 v[52:55], v[56:59], v[162:165], 0
	v_mfma_f32_16x16x32_bf16 v[48:51], v[144:147], v[162:165], 0
	v_mfma_f32_16x16x32_bf16 v[36:39], v[56:59], v[176:179], 0
	v_mfma_f32_16x16x32_bf16 v[32:35], v[144:147], v[176:179], 0
	v_mfma_f32_16x16x32_bf16 v[20:23], v[56:59], v[200:203], 0
	v_mfma_f32_16x16x32_bf16 v[16:19], v[144:147], v[200:203], 0
	v_mfma_f32_16x16x32_bf16 v[76:79], v[60:63], v[156:159], v[76:79]
	v_mfma_f32_16x16x32_bf16 v[72:75], v[148:151], v[156:159], v[72:75]
	v_mfma_f32_16x16x32_bf16 v[52:55], v[60:63], v[172:175], v[52:55]
	v_mfma_f32_16x16x32_bf16 v[48:51], v[148:151], v[172:175], v[48:51]
	v_mfma_f32_16x16x32_bf16 v[36:39], v[60:63], v[196:199], v[36:39]
	v_mfma_f32_16x16x32_bf16 v[32:35], v[148:151], v[196:199], v[32:35]
	v_mfma_f32_16x16x32_bf16 v[20:23], v[60:63], v[204:207], v[20:23]
	v_mfma_f32_16x16x32_bf16 v[16:19], v[148:151], v[204:207], v[16:19]
	s_barrier
	s_mov_b32 m0, s63
	s_add_u32 vcc_lo, s26, s82
	s_addc_u32 vcc_hi, s27, s83
	global_load_lds_dwordx4 v2, vcc
	s_mov_b32 m0, s62
	s_nop 0
	s_add_u32 vcc_lo, s26, s94
	s_addc_u32 vcc_hi, s27, s95
	global_load_lds_dwordx4 v2, vcc
	s_waitcnt vmcnt(6)
	s_barrier
	v_mfma_f32_16x16x32_bf16 v[44:47], v[208:211], v[162:165], 0
	v_mfma_f32_16x16x32_bf16 v[40:43], v[216:219], v[162:165], 0
	v_mfma_f32_16x16x32_bf16 v[28:31], v[208:211], v[176:179], 0
	v_mfma_f32_16x16x32_bf16 v[24:27], v[216:219], v[176:179], 0
	v_mfma_f32_16x16x32_bf16 v[12:15], v[208:211], v[200:203], 0
	v_mfma_f32_16x16x32_bf16 v[8:11], v[216:219], v[200:203], 0
	v_mfma_f32_16x16x32_bf16 v[56:59], v[208:211], v[152:155], 0
	v_mfma_f32_16x16x32_bf16 v[60:63], v[216:219], v[152:155], 0
	v_mfma_f32_16x16x32_bf16 v[44:47], v[212:215], v[172:175], v[44:47]
	v_mfma_f32_16x16x32_bf16 v[40:43], v[220:223], v[172:175], v[40:43]
	v_mfma_f32_16x16x32_bf16 v[28:31], v[212:215], v[196:199], v[28:31]
	v_mfma_f32_16x16x32_bf16 v[24:27], v[220:223], v[196:199], v[24:27]
	v_mfma_f32_16x16x32_bf16 v[12:15], v[212:215], v[204:207], v[12:15]
	v_mfma_f32_16x16x32_bf16 v[8:11], v[220:223], v[204:207], v[8:11]
	v_mfma_f32_16x16x32_bf16 v[56:59], v[212:215], v[156:159], v[56:59]
	v_mfma_f32_16x16x32_bf16 v[60:63], v[220:223], v[156:159], v[60:63]
	s_barrier
	ds_read_b128 v[64:67], v255 offset:32768
	ds_read_b128 v[68:71], v255 offset:33792
	ds_read_b128 v[144:147], v255 offset:34816
	ds_read_b128 v[148:151], v255 offset:35840
	s_mov_b32 m0, s51
	ds_read_b128 v[152:155], v184 offset:32768
	ds_read_b128 v[156:159], v184 offset:33792
	ds_read_b128 v[162:165], v184 offset:34816
	ds_read_b128 v[172:175], v184 offset:35840
	ds_read_b128 v[176:179], v184 offset:36864
	ds_read_b128 v[196:199], v184 offset:37888
	ds_read_b128 v[200:203], v184 offset:38912
	ds_read_b128 v[204:207], v184 offset:39936
	s_add_u32 vcc_lo, s34, s86
	s_addc_u32 vcc_hi, s35, s87
	global_load_lds_dwordx4 v160, vcc
	s_mov_b32 m0, s52
	s_nop 0
	s_add_u32 vcc_lo, s34, s96
	s_addc_u32 vcc_hi, s35, s97
	global_load_lds_dwordx4 v160, vcc
	s_waitcnt lgkmcnt(8)
	s_barrier
	s_waitcnt lgkmcnt(0)
	v_mfma_f32_16x16x32_bf16 v[140:143], v[64:67], v[152:155], v[140:143]
	v_mfma_f32_16x16x32_bf16 v[136:139], v[144:147], v[152:155], v[136:139]
	v_mfma_f32_16x16x32_bf16 v[124:127], v[64:67], v[162:165], v[124:127]
	v_mfma_f32_16x16x32_bf16 v[120:123], v[144:147], v[162:165], v[120:123]
	v_mfma_f32_16x16x32_bf16 v[108:111], v[64:67], v[176:179], v[108:111]
	v_mfma_f32_16x16x32_bf16 v[104:107], v[144:147], v[176:179], v[104:107]
	v_mfma_f32_16x16x32_bf16 v[92:95], v[64:67], v[200:203], v[92:95]
	v_mfma_f32_16x16x32_bf16 v[88:91], v[144:147], v[200:203], v[88:91]
	v_mfma_f32_16x16x32_bf16 v[140:143], v[68:71], v[156:159], v[140:143]
	v_mfma_f32_16x16x32_bf16 v[136:139], v[148:151], v[156:159], v[136:139]
	v_mfma_f32_16x16x32_bf16 v[124:127], v[68:71], v[172:175], v[124:127]
	v_mfma_f32_16x16x32_bf16 v[120:123], v[148:151], v[172:175], v[120:123]
	v_mfma_f32_16x16x32_bf16 v[108:111], v[68:71], v[196:199], v[108:111]
	v_mfma_f32_16x16x32_bf16 v[104:107], v[148:151], v[196:199], v[104:107]
	v_mfma_f32_16x16x32_bf16 v[92:95], v[68:71], v[204:207], v[92:95]
	v_mfma_f32_16x16x32_bf16 v[88:91], v[148:151], v[204:207], v[88:91]
	s_barrier
	s_mov_b32 m0, s30
	ds_read_b128 v[208:211], v255 offset:49152
	ds_read_b128 v[212:215], v255 offset:50176
	ds_read_b128 v[216:219], v255 offset:51200
	ds_read_b128 v[220:223], v255 offset:52224
	s_add_u32 vcc_lo, s26, s46
	s_addc_u32 vcc_hi, s27, s47
	global_load_lds_dwordx4 v2, vcc
	s_mov_b32 m0, s67
	s_nop 0
	s_add_u32 vcc_lo, s26, s70
	s_addc_u32 vcc_hi, s27, s71
	global_load_lds_dwordx4 v2, vcc
	s_barrier
	s_waitcnt lgkmcnt(0)
	v_mfma_f32_16x16x32_bf16 v[132:135], v[208:211], v[152:155], v[132:135]
	v_mfma_f32_16x16x32_bf16 v[128:131], v[216:219], v[152:155], v[128:131]
	v_mfma_f32_16x16x32_bf16 v[116:119], v[208:211], v[162:165], v[116:119]
	v_mfma_f32_16x16x32_bf16 v[112:115], v[216:219], v[162:165], v[112:115]
	v_mfma_f32_16x16x32_bf16 v[100:103], v[208:211], v[176:179], v[100:103]
	v_mfma_f32_16x16x32_bf16 v[96:99], v[216:219], v[176:179], v[96:99]
	v_mfma_f32_16x16x32_bf16 v[84:87], v[208:211], v[200:203], v[84:87]
	v_mfma_f32_16x16x32_bf16 v[80:83], v[216:219], v[200:203], v[80:83]
	v_mfma_f32_16x16x32_bf16 v[132:135], v[212:215], v[156:159], v[132:135]
	v_mfma_f32_16x16x32_bf16 v[128:131], v[220:223], v[156:159], v[128:131]
	v_mfma_f32_16x16x32_bf16 v[116:119], v[212:215], v[172:175], v[116:119]
	v_mfma_f32_16x16x32_bf16 v[112:115], v[220:223], v[172:175], v[112:115]
	v_mfma_f32_16x16x32_bf16 v[100:103], v[212:215], v[196:199], v[100:103]
	v_mfma_f32_16x16x32_bf16 v[96:99], v[220:223], v[196:199], v[96:99]
	v_mfma_f32_16x16x32_bf16 v[84:87], v[212:215], v[204:207], v[84:87]
	v_mfma_f32_16x16x32_bf16 v[80:83], v[220:223], v[204:207], v[80:83]
	s_barrier
; #define G_STAGE(bufoff, gbase, o0, h64) do { \
;         __builtin_amdgcn_global_load_lds((const unsigned*)((const char*)(gbase) + (o0)), (LAS unsigned*)(lds + (bufoff) + ldsw), 16, 0, 0); \
;         __builtin_amdgcn_global_load_lds((const unsigned*)((const char*)(gbase) + (h64) + (o0)), (LAS unsigned*)(lds + (bufoff) + ldsw + 8192), 16, 0, 0); } while (0)
; #define G_LDA(dst, b, h) do { _Pragma("unroll") for (int m = 0; m < 4; ++m) _Pragma("unroll") for (int k = 0; k < 2; ++k) dst[m][k] = *(const LAS bf16x8*)(lds + G_SA(b, h) + aoff + m * 2048 + k * 1024); } while (0)
; #define G_LDB(dst, b, h) do { _Pragma("unroll") for (int n = 0; n < 2; ++n) _Pragma("unroll") for (int k = 0; k < 2; ++k) dst[n][k] = *(const LAS bf16x8*)(lds + G_SB(b, h) + boff + n * 2048 + k * 1024); } while (0)
; #define G_WAIT_V(n) asm volatile("s_waitcnt vmcnt(" #n ")" ::: "memory")
; #define G_BAR __builtin_amdgcn_s_barrier()
;     ...
;         for (int t = 0; t < nt; t += 2) {
;             const bool last = (t == nt - 2);
;             const char* a1 = cA + (size_t)(t + 1) * ckA;
;             const char* a2 = last ? nA : cA + (size_t)(t + 2) * ckA; const char* b2 = last ? nB : cB + (size_t)(t + 2) * kB;
;             const char* a3 = a2 + ckA; const char* b3 = b2 + kB;
;             G_LDB(B0, 0, 0); G_SCHED; G_LDA(At, 0, 0); G_STAGE(G_SA(1, 1), a1 + chA, cA0, qA);
;             G_WAIT_L(8); G_BAR; G_WAIT_L(0); G_MMA(0, 0, At, B0); G_BAR; G_SCHED;
;             G_LDB(B1, 0, 1); G_STAGE(G_SB(0, 0), b2, cB0, qB);
;             G_BAR; G_WAIT_L(0); G_MMA(0, 1, At, B1); G_BAR;
;             G_LDA(At, 0, 1); G_STAGE(G_SA(0, 0), a2, cA0, qA);
;             G_BAR; G_WAIT_L(0); G_MMA(1, 0, At, B0); G_BAR; G_SCHED;
;             G_STAGE(G_SB(0, 1), b2 + chB, cB0, qB);
;             G_WAIT_V(6); G_BAR; G_MMA(1, 1, At, B1); G_BAR;
;             G_LDB(B0, 1, 0); G_SCHED; G_LDA(At, 1, 0); G_STAGE(G_SA(0, 1), a2 + chA, cA0, qA);
;             G_WAIT_L(8); G_BAR; G_WAIT_L(0); G_MMA(0, 0, At, B0); G_BAR; G_SCHED;
;             G_LDB(B1, 1, 1); G_STAGE(G_SB(1, 0), b3, cB0, qB);
;             G_BAR; G_WAIT_L(0); G_MMA(0, 1, At, B1); G_BAR;
;             G_LDA(At, 1, 1); G_STAGE(G_SA(1, 0), a3, cA0, qA);
;             G_BAR; G_WAIT_L(0); G_MMA(1, 0, At, B0); G_BAR; G_SCHED;
;             G_STAGE(G_SB(1, 1), b3 + chB, cB0, qB);
;             G_WAIT_V(6); G_BAR; G_MMA(1, 1, At, B1); G_BAR;
	s_mov_b32 m0, s53
	ds_read_b128 v[152:155], v184 offset:49152
	ds_read_b128 v[156:159], v184 offset:50176
	ds_read_b128 v[162:165], v184 offset:51200
	ds_read_b128 v[172:175], v184 offset:52224
	ds_read_b128 v[176:179], v184 offset:53248
	ds_read_b128 v[196:199], v184 offset:54272
	ds_read_b128 v[200:203], v184 offset:55296
	ds_read_b128 v[204:207], v184 offset:56320
	s_add_u32 vcc_lo, s34, s46
	s_addc_u32 vcc_hi, s35, s47
	global_load_lds_dwordx4 v160, vcc
	s_mov_b32 m0, s54
	s_nop 0
	s_add_u32 vcc_lo, s34, s68
	s_addc_u32 vcc_hi, s35, s69
	global_load_lds_dwordx4 v160, vcc
	s_barrier
	s_waitcnt lgkmcnt(0)
	v_mfma_f32_16x16x32_bf16 v[76:79], v[64:67], v[152:155], v[76:79]
	v_mfma_f32_16x16x32_bf16 v[72:75], v[144:147], v[152:155], v[72:75]
	v_mfma_f32_16x16x32_bf16 v[52:55], v[64:67], v[162:165], v[52:55]
	v_mfma_f32_16x16x32_bf16 v[48:51], v[144:147], v[162:165], v[48:51]
	v_mfma_f32_16x16x32_bf16 v[36:39], v[64:67], v[176:179], v[36:39]
	v_mfma_f32_16x16x32_bf16 v[32:35], v[144:147], v[176:179], v[32:35]
	v_mfma_f32_16x16x32_bf16 v[20:23], v[64:67], v[200:203], v[20:23]
	v_mfma_f32_16x16x32_bf16 v[16:19], v[144:147], v[200:203], v[16:19]
	v_mfma_f32_16x16x32_bf16 v[76:79], v[68:71], v[156:159], v[76:79]
	v_mfma_f32_16x16x32_bf16 v[72:75], v[148:151], v[156:159], v[72:75]
	v_mfma_f32_16x16x32_bf16 v[52:55], v[68:71], v[172:175], v[52:55]
	v_mfma_f32_16x16x32_bf16 v[48:51], v[148:151], v[172:175], v[48:51]
	v_mfma_f32_16x16x32_bf16 v[36:39], v[68:71], v[196:199], v[36:39]
	v_mfma_f32_16x16x32_bf16 v[32:35], v[148:151], v[196:199], v[32:35]
	v_mfma_f32_16x16x32_bf16 v[20:23], v[68:71], v[204:207], v[20:23]
	v_mfma_f32_16x16x32_bf16 v[16:19], v[148:151], v[204:207], v[16:19]
	s_barrier
	s_mov_b32 m0, s65
	s_add_u32 vcc_lo, s26, s84
	s_addc_u32 vcc_hi, s27, s85
	global_load_lds_dwordx4 v2, vcc
	s_mov_b32 m0, s64
	s_nop 0
	s_add_u32 vcc_lo, s26, s28
	s_addc_u32 vcc_hi, s27, s29
	global_load_lds_dwordx4 v2, vcc
	s_waitcnt vmcnt(6)
	s_barrier
	v_mfma_f32_16x16x32_bf16 v[56:59], v[208:211], v[152:155], v[56:59]
	v_mfma_f32_16x16x32_bf16 v[68:71], v[212:215], v[156:159], v[56:59]
	v_mfma_f32_16x16x32_bf16 v[56:59], v[216:219], v[152:155], v[60:63]
	v_mfma_f32_16x16x32_bf16 v[44:47], v[208:211], v[162:165], v[44:47]
	v_mfma_f32_16x16x32_bf16 v[40:43], v[216:219], v[162:165], v[40:43]
	v_mfma_f32_16x16x32_bf16 v[28:31], v[208:211], v[176:179], v[28:31]
	v_mfma_f32_16x16x32_bf16 v[24:27], v[216:219], v[176:179], v[24:27]
	v_mfma_f32_16x16x32_bf16 v[12:15], v[208:211], v[200:203], v[12:15]
	v_mfma_f32_16x16x32_bf16 v[8:11], v[216:219], v[200:203], v[8:11]
	v_mfma_f32_16x16x32_bf16 v[64:67], v[220:223], v[156:159], v[56:59]
	v_mfma_f32_16x16x32_bf16 v[44:47], v[212:215], v[172:175], v[44:47]
	v_mfma_f32_16x16x32_bf16 v[40:43], v[220:223], v[172:175], v[40:43]
	v_mfma_f32_16x16x32_bf16 v[28:31], v[212:215], v[196:199], v[28:31]
	v_mfma_f32_16x16x32_bf16 v[24:27], v[220:223], v[196:199], v[24:27]
	v_mfma_f32_16x16x32_bf16 v[12:15], v[212:215], v[204:207], v[12:15]
	v_mfma_f32_16x16x32_bf16 v[8:11], v[220:223], v[204:207], v[8:11]
	s_andn2_b64 vcc, exec, s[24:25]
	s_mov_b64 s[26:27], -1
	s_mov_b64 s[24:25], 0
	s_mov_b64 s[30:31], 0x100
	s_cbranch_vccz .Ldb_SSM2_cont
	s_branch .Ldb_SSM2_xl
.LBB0_742:
	s_add_u32 s36, s2, s30
	s_addc_u32 s37, s3, s31
	s_add_u32 s19, s36, 0x100
	s_addc_u32 s35, s37, 0
	s_and_b64 s[4:5], s[26:27], exec
	s_cselect_b32 s34, s12, s19
	s_cselect_b32 s35, s13, s35
	s_add_u32 s4, s20, s30
	s_addc_u32 s5, s21, s31
	s_add_u32 s19, s4, 0x100
	s_addc_u32 s30, s5, 0
	s_add_i32 s44, 0, 0x10000
	ds_read_b128 v[56:59], v255 offset:0
	ds_read_b128 v[60:63], v255 offset:1024
	ds_read_b128 v[144:147], v255 offset:2048
	ds_read_b128 v[148:151], v255 offset:3072
	s_and_b64 s[4:5], s[26:27], exec
	s_cselect_b32 s26, s16, s19
	s_cselect_b32 s27, s17, s30
	s_add_i32 s48, 0, 0x14000
	s_add_i32 s31, 0, 0x18000
	s_add_i32 s19, 0, 0x1c000
	s_add_i32 s49, s44, s38
	s_add_i32 s63, s48, s38
	s_add_i32 s30, s31, s38
	s_add_i32 s65, s19, s38
	s_add_i32 m0, s43, 0xc000
	s_add_i32 s45, s43, 0xe000
	s_add_i32 s66, s49, 0x2000
	s_add_i32 s62, s63, 0x2000
	s_add_i32 s67, s30, 0x2000
	s_add_i32 s64, s65, 0x2000
	s_mov_b64 s[4:5], 0x200080
	s_add_u32 vcc_lo, s36, s4
	s_addc_u32 vcc_hi, s37, s5
	s_mov_b64 s[4:5], 0x300080
	ds_read_b128 v[152:155], v184
	ds_read_b128 v[156:159], v184 offset:1024
	ds_read_b128 v[162:165], v184 offset:2048
	ds_read_b128 v[172:175], v184 offset:3072
	ds_read_b128 v[176:179], v184 offset:4096
	ds_read_b128 v[196:199], v184 offset:5120
	ds_read_b128 v[200:203], v184 offset:6144
	ds_read_b128 v[204:207], v184 offset:7168
	global_load_lds_dwordx4 v160, vcc
	s_mov_b32 m0, s45
	s_nop 0
	s_add_u32 vcc_lo, s36, s4
	s_addc_u32 vcc_hi, s37, s5
	global_load_lds_dwordx4 v160, vcc
	s_waitcnt lgkmcnt(8)
	s_barrier
	s_waitcnt lgkmcnt(0)
	v_mfma_f32_16x16x32_bf16 v[140:143], v[56:59], v[152:155], v[140:143]
	v_mfma_f32_16x16x32_bf16 v[136:139], v[144:147], v[152:155], v[136:139]
	v_mfma_f32_16x16x32_bf16 v[124:127], v[56:59], v[162:165], v[124:127]
	v_mfma_f32_16x16x32_bf16 v[120:123], v[144:147], v[162:165], v[120:123]
	v_mfma_f32_16x16x32_bf16 v[108:111], v[56:59], v[176:179], v[108:111]
	v_mfma_f32_16x16x32_bf16 v[104:107], v[144:147], v[176:179], v[104:107]
	v_mfma_f32_16x16x32_bf16 v[92:95], v[56:59], v[200:203], v[92:95]
	v_mfma_f32_16x16x32_bf16 v[88:91], v[144:147], v[200:203], v[88:91]
	v_mfma_f32_16x16x32_bf16 v[140:143], v[60:63], v[156:159], v[140:143]
	v_mfma_f32_16x16x32_bf16 v[136:139], v[148:151], v[156:159], v[136:139]
	v_mfma_f32_16x16x32_bf16 v[124:127], v[60:63], v[172:175], v[124:127]
	v_mfma_f32_16x16x32_bf16 v[120:123], v[148:151], v[172:175], v[120:123]
	v_mfma_f32_16x16x32_bf16 v[108:111], v[60:63], v[196:199], v[108:111]
	v_mfma_f32_16x16x32_bf16 v[104:107], v[148:151], v[196:199], v[104:107]
	v_mfma_f32_16x16x32_bf16 v[92:95], v[60:63], v[204:207], v[92:95]
	v_mfma_f32_16x16x32_bf16 v[88:91], v[148:151], v[204:207], v[88:91]
	s_barrier
; #define G_STAGE(bufoff, gbase, o0, h64) do { \
;         __builtin_amdgcn_global_load_lds((const unsigned*)((const char*)(gbase) + (o0)), (LAS unsigned*)(lds + (bufoff) + ldsw), 16, 0, 0); \
;         __builtin_amdgcn_global_load_lds((const unsigned*)((const char*)(gbase) + (h64) + (o0)), (LAS unsigned*)(lds + (bufoff) + ldsw + 8192), 16, 0, 0); } while (0)
; #define G_LDA(dst, b, h) do { _Pragma("unroll") for (int m = 0; m < 4; ++m) _Pragma("unroll") for (int k = 0; k < 2; ++k) dst[m][k] = *(const LAS bf16x8*)(lds + G_SA(b, h) + aoff + m * 2048 + k * 1024); } while (0)
; #define G_LDB(dst, b, h) do { _Pragma("unroll") for (int n = 0; n < 2; ++n) _Pragma("unroll") for (int k = 0; k < 2; ++k) dst[n][k] = *(const LAS bf16x8*)(lds + G_SB(b, h) + boff + n * 2048 + k * 1024); } while (0)
; #define G_WAIT_V(n) asm volatile("s_waitcnt vmcnt(" #n ")" ::: "memory")
; #define G_BAR __builtin_amdgcn_s_barrier()
;     ...
;         for (int t = 0; t < nt; t += 2) {
;             const bool last = (t == nt - 2);
;             const char* a1 = cA + (size_t)(t + 1) * ckA;
;             const char* a2 = last ? nA : cA + (size_t)(t + 2) * ckA; const char* b2 = last ? nB : cB + (size_t)(t + 2) * kB;
;             const char* a3 = a2 + ckA; const char* b3 = b2 + kB;
;             G_LDB(B0, 0, 0); G_SCHED; G_LDA(At, 0, 0); G_STAGE(G_SA(1, 1), a1 + chA, cA0, qA);
;             G_WAIT_L(8); G_BAR; G_WAIT_L(0); G_MMA(0, 0, At, B0); G_BAR; G_SCHED;
;             G_LDB(B1, 0, 1); G_STAGE(G_SB(0, 0), b2, cB0, qB);
;             G_BAR; G_WAIT_L(0); G_MMA(0, 1, At, B1); G_BAR;
;             G_LDA(At, 0, 1); G_STAGE(G_SA(0, 0), a2, cA0, qA);
;             G_BAR; G_WAIT_L(0); G_MMA(1, 0, At, B0); G_BAR; G_SCHED;
;             G_STAGE(G_SB(0, 1), b2 + chB, cB0, qB);
;             G_WAIT_V(6); G_BAR; G_MMA(1, 1, At, B1); G_BAR;
;             G_LDB(B0, 1, 0); G_SCHED; G_LDA(At, 1, 0); G_STAGE(G_SA(0, 1), a2 + chA, cA0, qA);
;             G_WAIT_L(8); G_BAR; G_WAIT_L(0); G_MMA(0, 0, At, B0); G_BAR; G_SCHED;
;             G_LDB(B1, 1, 1); G_STAGE(G_SB(1, 0), b3, cB0, qB);
;             G_BAR; G_WAIT_L(0); G_MMA(0, 1, At, B1); G_BAR;
;             G_LDA(At, 1, 1); G_STAGE(G_SA(1, 0), a3, cA0, qA);
;             G_BAR; G_WAIT_L(0); G_MMA(1, 0, At, B0); G_BAR; G_SCHED;
;             G_STAGE(G_SB(1, 1), b3 + chB, cB0, qB);
;             G_WAIT_V(6); G_BAR; G_MMA(1, 1, At, B1); G_BAR;
	s_mov_b32 m0, s49
	ds_read_b128 v[208:211], v255 offset:16384
	ds_read_b128 v[212:215], v255 offset:17408
	ds_read_b128 v[216:219], v255 offset:18432
	ds_read_b128 v[220:223], v255 offset:19456
	global_load_lds_dwordx4 v2, s[26:27]
	s_mov_b32 m0, s66
	s_nop 0
	s_add_u32 vcc_lo, s26, s92
	s_addc_u32 vcc_hi, s27, s93
	global_load_lds_dwordx4 v2, vcc
	s_barrier
	s_waitcnt lgkmcnt(0)
	v_mfma_f32_16x16x32_bf16 v[132:135], v[208:211], v[152:155], v[132:135]
	v_mfma_f32_16x16x32_bf16 v[128:131], v[216:219], v[152:155], v[128:131]
	v_mfma_f32_16x16x32_bf16 v[116:119], v[208:211], v[162:165], v[116:119]
	v_mfma_f32_16x16x32_bf16 v[112:115], v[216:219], v[162:165], v[112:115]
	v_mfma_f32_16x16x32_bf16 v[100:103], v[208:211], v[176:179], v[100:103]
	v_mfma_f32_16x16x32_bf16 v[96:99], v[216:219], v[176:179], v[96:99]
	v_mfma_f32_16x16x32_bf16 v[84:87], v[208:211], v[200:203], v[84:87]
	v_mfma_f32_16x16x32_bf16 v[80:83], v[216:219], v[200:203], v[80:83]
	v_mfma_f32_16x16x32_bf16 v[132:135], v[212:215], v[156:159], v[132:135]
	v_mfma_f32_16x16x32_bf16 v[128:131], v[220:223], v[156:159], v[128:131]
	v_mfma_f32_16x16x32_bf16 v[116:119], v[212:215], v[172:175], v[116:119]
	v_mfma_f32_16x16x32_bf16 v[112:115], v[220:223], v[172:175], v[112:115]
	v_mfma_f32_16x16x32_bf16 v[100:103], v[212:215], v[196:199], v[100:103]
	v_mfma_f32_16x16x32_bf16 v[96:99], v[220:223], v[196:199], v[96:99]
	v_mfma_f32_16x16x32_bf16 v[84:87], v[212:215], v[204:207], v[84:87]
	v_mfma_f32_16x16x32_bf16 v[80:83], v[220:223], v[204:207], v[80:83]
	s_barrier
	s_mov_b32 m0, s43
	ds_read_b128 v[152:155], v184 offset:16384
	ds_read_b128 v[156:159], v184 offset:17408
	ds_read_b128 v[162:165], v184 offset:18432
	ds_read_b128 v[172:175], v184 offset:19456
	ds_read_b128 v[176:179], v184 offset:20480
	ds_read_b128 v[196:199], v184 offset:21504
	ds_read_b128 v[200:203], v184 offset:22528
	ds_read_b128 v[204:207], v184 offset:23552
	global_load_lds_dwordx4 v160, s[34:35]
	s_mov_b32 m0, s50
	s_nop 0
	s_add_u32 vcc_lo, s34, s88
	s_addc_u32 vcc_hi, s35, s89
	global_load_lds_dwordx4 v160, vcc
	s_barrier
	s_waitcnt lgkmcnt(0)
	v_mfma_f32_16x16x32_bf16 v[76:79], v[56:59], v[152:155], v[76:79]
	v_mfma_f32_16x16x32_bf16 v[72:75], v[144:147], v[152:155], v[72:75]
	v_mfma_f32_16x16x32_bf16 v[52:55], v[56:59], v[162:165], v[52:55]
	v_mfma_f32_16x16x32_bf16 v[48:51], v[144:147], v[162:165], v[48:51]
	v_mfma_f32_16x16x32_bf16 v[36:39], v[56:59], v[176:179], v[36:39]
	v_mfma_f32_16x16x32_bf16 v[32:35], v[144:147], v[176:179], v[32:35]
	v_mfma_f32_16x16x32_bf16 v[20:23], v[56:59], v[200:203], v[20:23]
	v_mfma_f32_16x16x32_bf16 v[16:19], v[144:147], v[200:203], v[16:19]
	v_mfma_f32_16x16x32_bf16 v[76:79], v[60:63], v[156:159], v[76:79]
	v_mfma_f32_16x16x32_bf16 v[72:75], v[148:151], v[156:159], v[72:75]
	v_mfma_f32_16x16x32_bf16 v[52:55], v[60:63], v[172:175], v[52:55]
	v_mfma_f32_16x16x32_bf16 v[48:51], v[148:151], v[172:175], v[48:51]
	v_mfma_f32_16x16x32_bf16 v[36:39], v[60:63], v[196:199], v[36:39]
	v_mfma_f32_16x16x32_bf16 v[32:35], v[148:151], v[196:199], v[32:35]
	v_mfma_f32_16x16x32_bf16 v[20:23], v[60:63], v[204:207], v[20:23]
	v_mfma_f32_16x16x32_bf16 v[16:19], v[148:151], v[204:207], v[16:19]
	s_barrier
	s_mov_b32 m0, s63
	s_add_u32 vcc_lo, s26, s82
	s_addc_u32 vcc_hi, s27, s83
	global_load_lds_dwordx4 v2, vcc
	s_mov_b32 m0, s62
	s_nop 0
	s_add_u32 vcc_lo, s26, s94
	s_addc_u32 vcc_hi, s27, s95
	global_load_lds_dwordx4 v2, vcc
	s_waitcnt vmcnt(6)
	s_barrier
	v_mfma_f32_16x16x32_bf16 v[44:47], v[208:211], v[162:165], v[44:47]
	v_mfma_f32_16x16x32_bf16 v[40:43], v[216:219], v[162:165], v[40:43]
	v_mfma_f32_16x16x32_bf16 v[28:31], v[208:211], v[176:179], v[28:31]
	v_mfma_f32_16x16x32_bf16 v[24:27], v[216:219], v[176:179], v[24:27]
	v_mfma_f32_16x16x32_bf16 v[12:15], v[208:211], v[200:203], v[12:15]
	v_mfma_f32_16x16x32_bf16 v[8:11], v[216:219], v[200:203], v[8:11]
	v_mfma_f32_16x16x32_bf16 v[56:59], v[208:211], v[152:155], v[68:71]
	v_mfma_f32_16x16x32_bf16 v[60:63], v[216:219], v[152:155], v[64:67]
	v_mfma_f32_16x16x32_bf16 v[44:47], v[212:215], v[172:175], v[44:47]
	v_mfma_f32_16x16x32_bf16 v[40:43], v[220:223], v[172:175], v[40:43]
	v_mfma_f32_16x16x32_bf16 v[28:31], v[212:215], v[196:199], v[28:31]
	v_mfma_f32_16x16x32_bf16 v[24:27], v[220:223], v[196:199], v[24:27]
	v_mfma_f32_16x16x32_bf16 v[12:15], v[212:215], v[204:207], v[12:15]
	v_mfma_f32_16x16x32_bf16 v[8:11], v[220:223], v[204:207], v[8:11]
	v_mfma_f32_16x16x32_bf16 v[56:59], v[212:215], v[156:159], v[56:59]
	v_mfma_f32_16x16x32_bf16 v[60:63], v[220:223], v[156:159], v[60:63]
	s_barrier
	ds_read_b128 v[64:67], v255 offset:32768
	ds_read_b128 v[68:71], v255 offset:33792
	ds_read_b128 v[144:147], v255 offset:34816
	ds_read_b128 v[148:151], v255 offset:35840
	s_mov_b32 m0, s51
	ds_read_b128 v[152:155], v184 offset:32768
	ds_read_b128 v[156:159], v184 offset:33792
	ds_read_b128 v[162:165], v184 offset:34816
	ds_read_b128 v[172:175], v184 offset:35840
	ds_read_b128 v[176:179], v184 offset:36864
	ds_read_b128 v[196:199], v184 offset:37888
	ds_read_b128 v[200:203], v184 offset:38912
	ds_read_b128 v[204:207], v184 offset:39936
	s_add_u32 vcc_lo, s34, s86
	s_addc_u32 vcc_hi, s35, s87
	global_load_lds_dwordx4 v160, vcc
	s_mov_b32 m0, s52
	s_nop 0
	s_add_u32 vcc_lo, s34, s96
	s_addc_u32 vcc_hi, s35, s97
	global_load_lds_dwordx4 v160, vcc
	s_waitcnt lgkmcnt(8)
	s_barrier
; #define G_STAGE(bufoff, gbase, o0, h64) do { \
;         __builtin_amdgcn_global_load_lds((const unsigned*)((const char*)(gbase) + (o0)), (LAS unsigned*)(lds + (bufoff) + ldsw), 16, 0, 0); \
;         __builtin_amdgcn_global_load_lds((const unsigned*)((const char*)(gbase) + (h64) + (o0)), (LAS unsigned*)(lds + (bufoff) + ldsw + 8192), 16, 0, 0); } while (0)
; #define G_LDA(dst, b, h) do { _Pragma("unroll") for (int m = 0; m < 4; ++m) _Pragma("unroll") for (int k = 0; k < 2; ++k) dst[m][k] = *(const LAS bf16x8*)(lds + G_SA(b, h) + aoff + m * 2048 + k * 1024); } while (0)
; #define G_LDB(dst, b, h) do { _Pragma("unroll") for (int n = 0; n < 2; ++n) _Pragma("unroll") for (int k = 0; k < 2; ++k) dst[n][k] = *(const LAS bf16x8*)(lds + G_SB(b, h) + boff + n * 2048 + k * 1024); } while (0)
; #define G_WAIT_V(n) asm volatile("s_waitcnt vmcnt(" #n ")" ::: "memory")
; #define G_BAR __builtin_amdgcn_s_barrier()
;     ...
;         for (int t = 0; t < nt; t += 2) {
;             const bool last = (t == nt - 2);
;             const char* a1 = cA + (size_t)(t + 1) * ckA;
;             const char* a2 = last ? nA : cA + (size_t)(t + 2) * ckA; const char* b2 = last ? nB : cB + (size_t)(t + 2) * kB;
;             const char* a3 = a2 + ckA; const char* b3 = b2 + kB;
;             G_LDB(B0, 0, 0); G_SCHED; G_LDA(At, 0, 0); G_STAGE(G_SA(1, 1), a1 + chA, cA0, qA);
;             G_WAIT_L(8); G_BAR; G_WAIT_L(0); G_MMA(0, 0, At, B0); G_BAR; G_SCHED;
;             G_LDB(B1, 0, 1); G_STAGE(G_SB(0, 0), b2, cB0, qB);
;             G_BAR; G_WAIT_L(0); G_MMA(0, 1, At, B1); G_BAR;
;             G_LDA(At, 0, 1); G_STAGE(G_SA(0, 0), a2, cA0, qA);
;             G_BAR; G_WAIT_L(0); G_MMA(1, 0, At, B0); G_BAR; G_SCHED;
;             G_STAGE(G_SB(0, 1), b2 + chB, cB0, qB);
;             G_WAIT_V(6); G_BAR; G_MMA(1, 1, At, B1); G_BAR;
;             G_LDB(B0, 1, 0); G_SCHED; G_LDA(At, 1, 0); G_STAGE(G_SA(0, 1), a2 + chA, cA0, qA);
;             G_WAIT_L(8); G_BAR; G_WAIT_L(0); G_MMA(0, 0, At, B0); G_BAR; G_SCHED;
;             G_LDB(B1, 1, 1); G_STAGE(G_SB(1, 0), b3, cB0, qB);
;             G_BAR; G_WAIT_L(0); G_MMA(0, 1, At, B1); G_BAR;
;             G_LDA(At, 1, 1); G_STAGE(G_SA(1, 0), a3, cA0, qA);
;             G_BAR; G_WAIT_L(0); G_MMA(1, 0, At, B0); G_BAR; G_SCHED;
;             G_STAGE(G_SB(1, 1), b3 + chB, cB0, qB);
;             G_WAIT_V(6); G_BAR; G_MMA(1, 1, At, B1); G_BAR;
	s_waitcnt lgkmcnt(0)
	v_mfma_f32_16x16x32_bf16 v[140:143], v[64:67], v[152:155], v[140:143]
	v_mfma_f32_16x16x32_bf16 v[136:139], v[144:147], v[152:155], v[136:139]
	v_mfma_f32_16x16x32_bf16 v[124:127], v[64:67], v[162:165], v[124:127]
	v_mfma_f32_16x16x32_bf16 v[120:123], v[144:147], v[162:165], v[120:123]
	v_mfma_f32_16x16x32_bf16 v[108:111], v[64:67], v[176:179], v[108:111]
	v_mfma_f32_16x16x32_bf16 v[104:107], v[144:147], v[176:179], v[104:107]
	v_mfma_f32_16x16x32_bf16 v[92:95], v[64:67], v[200:203], v[92:95]
	v_mfma_f32_16x16x32_bf16 v[88:91], v[144:147], v[200:203], v[88:91]
	v_mfma_f32_16x16x32_bf16 v[140:143], v[68:71], v[156:159], v[140:143]
	v_mfma_f32_16x16x32_bf16 v[136:139], v[148:151], v[156:159], v[136:139]
	v_mfma_f32_16x16x32_bf16 v[124:127], v[68:71], v[172:175], v[124:127]
	v_mfma_f32_16x16x32_bf16 v[120:123], v[148:151], v[172:175], v[120:123]
	v_mfma_f32_16x16x32_bf16 v[108:111], v[68:71], v[196:199], v[108:111]
	v_mfma_f32_16x16x32_bf16 v[104:107], v[148:151], v[196:199], v[104:107]
	v_mfma_f32_16x16x32_bf16 v[92:95], v[68:71], v[204:207], v[92:95]
	v_mfma_f32_16x16x32_bf16 v[88:91], v[148:151], v[204:207], v[88:91]
	s_barrier
	s_mov_b32 m0, s30
	ds_read_b128 v[208:211], v255 offset:49152
	ds_read_b128 v[212:215], v255 offset:50176
	ds_read_b128 v[216:219], v255 offset:51200
	ds_read_b128 v[220:223], v255 offset:52224
	s_add_u32 vcc_lo, s26, s46
	s_addc_u32 vcc_hi, s27, s47
	global_load_lds_dwordx4 v2, vcc
	s_mov_b32 m0, s67
	s_nop 0
	s_add_u32 vcc_lo, s26, s70
	s_addc_u32 vcc_hi, s27, s71
	global_load_lds_dwordx4 v2, vcc
	s_barrier
	s_waitcnt lgkmcnt(0)
	v_mfma_f32_16x16x32_bf16 v[132:135], v[208:211], v[152:155], v[132:135]
	v_mfma_f32_16x16x32_bf16 v[128:131], v[216:219], v[152:155], v[128:131]
	v_mfma_f32_16x16x32_bf16 v[116:119], v[208:211], v[162:165], v[116:119]
	v_mfma_f32_16x16x32_bf16 v[112:115], v[216:219], v[162:165], v[112:115]
	v_mfma_f32_16x16x32_bf16 v[100:103], v[208:211], v[176:179], v[100:103]
	v_mfma_f32_16x16x32_bf16 v[96:99], v[216:219], v[176:179], v[96:99]
	v_mfma_f32_16x16x32_bf16 v[84:87], v[208:211], v[200:203], v[84:87]
	v_mfma_f32_16x16x32_bf16 v[80:83], v[216:219], v[200:203], v[80:83]
	v_mfma_f32_16x16x32_bf16 v[132:135], v[212:215], v[156:159], v[132:135]
	v_mfma_f32_16x16x32_bf16 v[128:131], v[220:223], v[156:159], v[128:131]
	v_mfma_f32_16x16x32_bf16 v[116:119], v[212:215], v[172:175], v[116:119]
	v_mfma_f32_16x16x32_bf16 v[112:115], v[220:223], v[172:175], v[112:115]
	v_mfma_f32_16x16x32_bf16 v[100:103], v[212:215], v[196:199], v[100:103]
	v_mfma_f32_16x16x32_bf16 v[96:99], v[220:223], v[196:199], v[96:99]
	v_mfma_f32_16x16x32_bf16 v[84:87], v[212:215], v[204:207], v[84:87]
	v_mfma_f32_16x16x32_bf16 v[80:83], v[220:223], v[204:207], v[80:83]
	s_barrier
	s_mov_b32 m0, s53
	ds_read_b128 v[152:155], v184 offset:49152
	ds_read_b128 v[156:159], v184 offset:50176
	ds_read_b128 v[162:165], v184 offset:51200
	ds_read_b128 v[172:175], v184 offset:52224
	ds_read_b128 v[176:179], v184 offset:53248
	ds_read_b128 v[196:199], v184 offset:54272
	ds_read_b128 v[200:203], v184 offset:55296
	ds_read_b128 v[204:207], v184 offset:56320
	s_add_u32 vcc_lo, s34, s46
	s_addc_u32 vcc_hi, s35, s47
	global_load_lds_dwordx4 v160, vcc
	s_mov_b32 m0, s54
	s_nop 0
	s_add_u32 vcc_lo, s34, s68
	s_addc_u32 vcc_hi, s35, s69
	global_load_lds_dwordx4 v160, vcc
	s_barrier
	s_waitcnt lgkmcnt(0)
	v_mfma_f32_16x16x32_bf16 v[76:79], v[64:67], v[152:155], v[76:79]
	v_mfma_f32_16x16x32_bf16 v[72:75], v[144:147], v[152:155], v[72:75]
	v_mfma_f32_16x16x32_bf16 v[52:55], v[64:67], v[162:165], v[52:55]
	v_mfma_f32_16x16x32_bf16 v[48:51], v[144:147], v[162:165], v[48:51]
	v_mfma_f32_16x16x32_bf16 v[36:39], v[64:67], v[176:179], v[36:39]
	v_mfma_f32_16x16x32_bf16 v[32:35], v[144:147], v[176:179], v[32:35]
	v_mfma_f32_16x16x32_bf16 v[20:23], v[64:67], v[200:203], v[20:23]
	v_mfma_f32_16x16x32_bf16 v[16:19], v[144:147], v[200:203], v[16:19]
	v_mfma_f32_16x16x32_bf16 v[76:79], v[68:71], v[156:159], v[76:79]
	v_mfma_f32_16x16x32_bf16 v[72:75], v[148:151], v[156:159], v[72:75]
	v_mfma_f32_16x16x32_bf16 v[52:55], v[68:71], v[172:175], v[52:55]
	v_mfma_f32_16x16x32_bf16 v[48:51], v[148:151], v[172:175], v[48:51]
	v_mfma_f32_16x16x32_bf16 v[36:39], v[68:71], v[196:199], v[36:39]
	v_mfma_f32_16x16x32_bf16 v[32:35], v[148:151], v[196:199], v[32:35]
	v_mfma_f32_16x16x32_bf16 v[20:23], v[68:71], v[204:207], v[20:23]
	v_mfma_f32_16x16x32_bf16 v[16:19], v[148:151], v[204:207], v[16:19]
	s_barrier
	s_mov_b32 m0, s65
	s_add_u32 vcc_lo, s26, s84
	s_addc_u32 vcc_hi, s27, s85
	global_load_lds_dwordx4 v2, vcc
	s_mov_b32 m0, s64
	s_nop 0
	s_add_u32 vcc_lo, s26, s28
	s_addc_u32 vcc_hi, s27, s29
	global_load_lds_dwordx4 v2, vcc
	s_waitcnt vmcnt(6)
	s_barrier
	v_mfma_f32_16x16x32_bf16 v[56:59], v[208:211], v[152:155], v[56:59]
	v_mfma_f32_16x16x32_bf16 v[68:71], v[212:215], v[156:159], v[56:59]
	v_mfma_f32_16x16x32_bf16 v[56:59], v[216:219], v[152:155], v[60:63]
	v_mfma_f32_16x16x32_bf16 v[44:47], v[208:211], v[162:165], v[44:47]
	v_mfma_f32_16x16x32_bf16 v[40:43], v[216:219], v[162:165], v[40:43]
	v_mfma_f32_16x16x32_bf16 v[28:31], v[208:211], v[176:179], v[28:31]
	v_mfma_f32_16x16x32_bf16 v[24:27], v[216:219], v[176:179], v[24:27]
	v_mfma_f32_16x16x32_bf16 v[12:15], v[208:211], v[200:203], v[12:15]
	v_mfma_f32_16x16x32_bf16 v[8:11], v[216:219], v[200:203], v[8:11]
	v_mfma_f32_16x16x32_bf16 v[64:67], v[220:223], v[156:159], v[56:59]
	v_mfma_f32_16x16x32_bf16 v[44:47], v[212:215], v[172:175], v[44:47]
	v_mfma_f32_16x16x32_bf16 v[40:43], v[220:223], v[172:175], v[40:43]
	v_mfma_f32_16x16x32_bf16 v[28:31], v[212:215], v[196:199], v[28:31]
	v_mfma_f32_16x16x32_bf16 v[24:27], v[220:223], v[196:199], v[24:27]
	v_mfma_f32_16x16x32_bf16 v[12:15], v[212:215], v[204:207], v[12:15]
	v_mfma_f32_16x16x32_bf16 v[8:11], v[220:223], v[204:207], v[8:11]
	s_andn2_b64 vcc, exec, s[24:25]
	s_mov_b64 s[26:27], -1
	s_mov_b64 s[24:25], 0
	s_mov_b64 s[30:31], 0x100
	s_cbranch_vccz .Ldb_SSM2_cont
